# GLU half tiles also read the bf16 Y5 copy through the 16x16x32 half-tile k-loop
# speedup vs baseline: 1.0200x; 1.0026x over previous
.LBB0_647:
	s_cmpk_gt_i32 s22, 0x1ff
	s_mov_b64 s[10:11], -1
	s_cbranch_scc0 .LBB0_665
	s_lshl_b32 s10, s22, 4
	s_add_i32 s10, s10, 0x7fffe000
	s_and_b32 s12, s10, 0x7fffffc0
	s_addk_i32 s12, 0x4000
	v_or_b32_e32 v0, s12, v105
	v_lshlrev_b32_e32 v16, 11, v0
	v_mov_b32_e32 v17, v67
	v_lshl_add_u64 v[30:31], v[68:69], 0, v[16:17]
	s_lshl_b32 s10, s22, 7
	s_and_b32 s14, s10, 0x180
	v_add_lshl_u32 v66, s14, v105, 10
	v_lshl_add_u64 v[74:75], v[70:71], 0, v[66:67]
	v_readlane_b32 s98, v238, 32
	v_readlane_b32 s99, v238, 33
	v_readfirstlane_b32 s100, v70
	v_readfirstlane_b32 s101, v71
	s_mul_i32 s15, s12, 0x1200
	s_add_u32 s98, s98, s15
	s_addc_u32 s99, s99, 0
	s_lshl_b32 s15, s14, 10
	s_add_u32 s100, s100, s15
	s_addc_u32 s101, s101, 0
	v_lshrrev_b32_e32 v246, 3, v100
	v_and_b32_e32 v247, 7, v100
	v_bfe_u32 v244, v100, 4, 3
	v_xor_b32_e32 v244, v244, v247
	v_lshlrev_b32_e32 v244, 4, v244
	v_lshl_or_b32 v153, v246, 7, v244
	v_lshlrev_b32_e32 v245, 4, v247
	v_mul_u32_u24_e32 v116, 0x1200, v246
	v_add_u32_e32 v116, v116, v245
	v_add_u32_e32 v122, 0x24000, v116
	v_mul_u32_u24_e32 v123, 0x400, v246
	v_add_u32_e32 v123, v123, v245
	v_add_u32_e32 v124, 0x8000, v123
	v_add_u32_e32 v150, 0x10000, v123
	v_add_u32_e32 v151, 0x18000, v123
	v_and_b32_e32 v244, 15, v100
	v_bfe_u32 v245, v100, 4, 2
	v_bfe_u32 v246, v100, 1, 3
	v_xor_b32_e32 v247, v245, v246
	v_lshlrev_b32_e32 v247, 4, v247
	v_lshl_or_b32 v247, v244, 7, v247
	v_bfe_u32 v246, v100, 7, 1
	v_lshl_add_u32 v239, v246, 12, v247
	v_xor_b32_e32 v240, 64, v239
	v_bfe_u32 v246, v100, 6, 1
	v_lshl_add_u32 v241, v246, 13, v247
	v_add_u32_e32 v241, 0x4000, v241
	v_xor_b32_e32 v242, 64, v241
	v_bfe_u32 v247, v100, 7, 1
	v_lshlrev_b32_e32 v247, 5, v247
	v_lshl_add_u32 v247, v245, 2, v247
	v_mul_u32_u24_e32 v247, 0x84, v247
	v_lshl_add_u32 v247, v246, 6, v247
	v_add_u32_e32 v247, v247, v244
	v_lshlrev_b32_e32 v243, 2, v247
	global_load_dwordx4 v[138:141], v116, s[98:99]
	global_load_dwordx4 v[142:145], v122, s[98:99]
	global_load_dwordx4 v[154:157], v123, s[100:101]
	global_load_dwordx4 v[158:161], v124, s[100:101]
	global_load_dwordx4 v[162:165], v150, s[100:101]
	global_load_dwordx4 v[166:169], v151, s[100:101]
	global_load_dwordx4 v[170:173], v116, s[98:99] offset:128
	global_load_dwordx4 v[174:177], v122, s[98:99] offset:128
	global_load_dwordx4 v[178:181], v123, s[100:101] offset:128
	global_load_dwordx4 v[182:185], v124, s[100:101] offset:128
	global_load_dwordx4 v[186:189], v150, s[100:101] offset:128
	global_load_dwordx4 v[190:193], v151, s[100:101] offset:128
	s_barrier
	s_waitcnt vmcnt(6)
	ds_write_b128 v153, v[138:141]
	ds_write_b128 v153, v[142:145] offset:4096
	ds_write_b128 v153, v[154:157] offset:16384
	ds_write_b128 v153, v[158:161] offset:20480
	ds_write_b128 v153, v[162:165] offset:24576
	ds_write_b128 v153, v[166:169] offset:28672
	global_load_dwordx4 v[138:141], v116, s[98:99] offset:256
	global_load_dwordx4 v[142:145], v122, s[98:99] offset:256
	global_load_dwordx4 v[154:157], v123, s[100:101] offset:256
	global_load_dwordx4 v[158:161], v124, s[100:101] offset:256
	global_load_dwordx4 v[162:165], v150, s[100:101] offset:256
	global_load_dwordx4 v[166:169], v151, s[100:101] offset:256
	s_waitcnt lgkmcnt(0)
	s_barrier
	ds_read_b128 v[32:35], v239
	ds_read_b128 v[40:43], v241
	ds_read_b128 v[44:47], v241 offset:2048
	ds_read_b128 v[48:51], v241 offset:4096
	ds_read_b128 v[52:55], v241 offset:6144
	ds_read_b128 v[36:39], v239 offset:2048
	s_waitcnt lgkmcnt(4)
	v_mfma_f32_16x16x32_bf16 v[0:3], v[32:35], v[40:43], 0
	ds_read_b128 v[56:59], v240
	s_waitcnt lgkmcnt(4)
	v_mfma_f32_16x16x32_bf16 v[4:7], v[32:35], v[44:47], 0
	ds_read_b128 v[118:121], v242
	s_waitcnt lgkmcnt(4)
	v_mfma_f32_16x16x32_bf16 v[8:11], v[32:35], v[48:51], 0
	ds_read_b128 v[126:129], v242 offset:2048
	s_waitcnt lgkmcnt(4)
	v_mfma_f32_16x16x32_bf16 v[12:15], v[32:35], v[52:55], 0
	ds_read_b128 v[130:133], v242 offset:4096
	s_waitcnt lgkmcnt(4)
	v_mfma_f32_16x16x32_bf16 v[16:19], v[36:39], v[40:43], 0
	ds_read_b128 v[134:137], v242 offset:6144
	v_mfma_f32_16x16x32_bf16 v[20:23], v[36:39], v[44:47], 0
	ds_read_b128 v[60:63], v240 offset:2048
	v_mfma_f32_16x16x32_bf16 v[24:27], v[36:39], v[48:51], 0
	v_mfma_f32_16x16x32_bf16 v[28:31], v[36:39], v[52:55], 0
	s_waitcnt lgkmcnt(4)
	v_mfma_f32_16x16x32_bf16 v[0:3], v[56:59], v[118:121], v[0:3]
	s_waitcnt vmcnt(6)
	ds_write_b128 v153, v[170:173] offset:32768
	s_waitcnt lgkmcnt(4)
	v_mfma_f32_16x16x32_bf16 v[4:7], v[56:59], v[126:129], v[4:7]
	ds_write_b128 v153, v[174:177] offset:36864
	s_waitcnt lgkmcnt(4)
	v_mfma_f32_16x16x32_bf16 v[8:11], v[56:59], v[130:133], v[8:11]
	ds_write_b128 v153, v[178:181] offset:49152
	global_load_dwordx4 v[170:173], v116, s[98:99] offset:384
	s_waitcnt lgkmcnt(4)
	v_mfma_f32_16x16x32_bf16 v[12:15], v[56:59], v[134:137], v[12:15]
	ds_write_b128 v153, v[182:185] offset:53248
	global_load_dwordx4 v[174:177], v122, s[98:99] offset:384
	s_waitcnt lgkmcnt(4)
	v_mfma_f32_16x16x32_bf16 v[16:19], v[60:63], v[118:121], v[16:19]
	ds_write_b128 v153, v[186:189] offset:57344
	global_load_dwordx4 v[178:181], v123, s[100:101] offset:384
	v_mfma_f32_16x16x32_bf16 v[20:23], v[60:63], v[126:129], v[20:23]
	ds_write_b128 v153, v[190:193] offset:61440
	global_load_dwordx4 v[182:185], v124, s[100:101] offset:384
	v_mfma_f32_16x16x32_bf16 v[24:27], v[60:63], v[130:133], v[24:27]
	global_load_dwordx4 v[186:189], v150, s[100:101] offset:384
	v_mfma_f32_16x16x32_bf16 v[28:31], v[60:63], v[134:137], v[28:31]
	global_load_dwordx4 v[190:193], v151, s[100:101] offset:384
	s_waitcnt lgkmcnt(0)
	s_barrier
	ds_read_b128 v[32:35], v239 offset:32768
	ds_read_b128 v[40:43], v241 offset:32768
	ds_read_b128 v[44:47], v241 offset:34816
	ds_read_b128 v[48:51], v241 offset:36864
	ds_read_b128 v[52:55], v241 offset:38912
	ds_read_b128 v[36:39], v239 offset:34816
	s_waitcnt lgkmcnt(4)
	v_mfma_f32_16x16x32_bf16 v[0:3], v[32:35], v[40:43], v[0:3]
	ds_read_b128 v[56:59], v240 offset:32768
	s_waitcnt lgkmcnt(4)
	v_mfma_f32_16x16x32_bf16 v[4:7], v[32:35], v[44:47], v[4:7]
	ds_read_b128 v[118:121], v242 offset:32768
	s_waitcnt lgkmcnt(4)
	v_mfma_f32_16x16x32_bf16 v[8:11], v[32:35], v[48:51], v[8:11]
	ds_read_b128 v[126:129], v242 offset:34816
	s_waitcnt lgkmcnt(4)
	v_mfma_f32_16x16x32_bf16 v[12:15], v[32:35], v[52:55], v[12:15]
	ds_read_b128 v[130:133], v242 offset:36864
	s_waitcnt lgkmcnt(4)
	v_mfma_f32_16x16x32_bf16 v[16:19], v[36:39], v[40:43], v[16:19]
	ds_read_b128 v[134:137], v242 offset:38912
	v_mfma_f32_16x16x32_bf16 v[20:23], v[36:39], v[44:47], v[20:23]
	ds_read_b128 v[60:63], v240 offset:34816
	v_mfma_f32_16x16x32_bf16 v[24:27], v[36:39], v[48:51], v[24:27]
	v_mfma_f32_16x16x32_bf16 v[28:31], v[36:39], v[52:55], v[28:31]
	s_waitcnt lgkmcnt(4)
	v_mfma_f32_16x16x32_bf16 v[0:3], v[56:59], v[118:121], v[0:3]
	s_waitcnt vmcnt(6)
	ds_write_b128 v153, v[138:141]
	s_waitcnt lgkmcnt(4)
	v_mfma_f32_16x16x32_bf16 v[4:7], v[56:59], v[126:129], v[4:7]
	ds_write_b128 v153, v[142:145] offset:4096
	s_waitcnt lgkmcnt(4)
	v_mfma_f32_16x16x32_bf16 v[8:11], v[56:59], v[130:133], v[8:11]
	ds_write_b128 v153, v[154:157] offset:16384
	global_load_dwordx4 v[138:141], v116, s[98:99] offset:512
	s_waitcnt lgkmcnt(4)
	v_mfma_f32_16x16x32_bf16 v[12:15], v[56:59], v[134:137], v[12:15]
	ds_write_b128 v153, v[158:161] offset:20480
	global_load_dwordx4 v[142:145], v122, s[98:99] offset:512
	s_waitcnt lgkmcnt(4)
	v_mfma_f32_16x16x32_bf16 v[16:19], v[60:63], v[118:121], v[16:19]
	ds_write_b128 v153, v[162:165] offset:24576
	global_load_dwordx4 v[154:157], v123, s[100:101] offset:512
	v_mfma_f32_16x16x32_bf16 v[20:23], v[60:63], v[126:129], v[20:23]
	ds_write_b128 v153, v[166:169] offset:28672
	global_load_dwordx4 v[158:161], v124, s[100:101] offset:512
	v_mfma_f32_16x16x32_bf16 v[24:27], v[60:63], v[130:133], v[24:27]
	global_load_dwordx4 v[162:165], v150, s[100:101] offset:512
	v_mfma_f32_16x16x32_bf16 v[28:31], v[60:63], v[134:137], v[28:31]
	global_load_dwordx4 v[166:169], v151, s[100:101] offset:512
	s_waitcnt lgkmcnt(0)
	s_barrier
	ds_read_b128 v[32:35], v239
	ds_read_b128 v[40:43], v241
	ds_read_b128 v[44:47], v241 offset:2048
	ds_read_b128 v[48:51], v241 offset:4096
	ds_read_b128 v[52:55], v241 offset:6144
	ds_read_b128 v[36:39], v239 offset:2048
	s_waitcnt lgkmcnt(4)
	v_mfma_f32_16x16x32_bf16 v[0:3], v[32:35], v[40:43], v[0:3]
	ds_read_b128 v[56:59], v240
	s_waitcnt lgkmcnt(4)
	v_mfma_f32_16x16x32_bf16 v[4:7], v[32:35], v[44:47], v[4:7]
	ds_read_b128 v[118:121], v242
	s_waitcnt lgkmcnt(4)
	v_mfma_f32_16x16x32_bf16 v[8:11], v[32:35], v[48:51], v[8:11]
	ds_read_b128 v[126:129], v242 offset:2048
	s_waitcnt lgkmcnt(4)
	v_mfma_f32_16x16x32_bf16 v[12:15], v[32:35], v[52:55], v[12:15]
	ds_read_b128 v[130:133], v242 offset:4096
	s_waitcnt lgkmcnt(4)
	v_mfma_f32_16x16x32_bf16 v[16:19], v[36:39], v[40:43], v[16:19]
	ds_read_b128 v[134:137], v242 offset:6144
	v_mfma_f32_16x16x32_bf16 v[20:23], v[36:39], v[44:47], v[20:23]
	ds_read_b128 v[60:63], v240 offset:2048
	v_mfma_f32_16x16x32_bf16 v[24:27], v[36:39], v[48:51], v[24:27]
	v_mfma_f32_16x16x32_bf16 v[28:31], v[36:39], v[52:55], v[28:31]
	s_waitcnt lgkmcnt(4)
	v_mfma_f32_16x16x32_bf16 v[0:3], v[56:59], v[118:121], v[0:3]
	s_waitcnt vmcnt(6)
	ds_write_b128 v153, v[170:173] offset:32768
	s_waitcnt lgkmcnt(4)
	v_mfma_f32_16x16x32_bf16 v[4:7], v[56:59], v[126:129], v[4:7]
	ds_write_b128 v153, v[174:177] offset:36864
	s_waitcnt lgkmcnt(4)
	v_mfma_f32_16x16x32_bf16 v[8:11], v[56:59], v[130:133], v[8:11]
	ds_write_b128 v153, v[178:181] offset:49152
	global_load_dwordx4 v[170:173], v116, s[98:99] offset:640
	s_waitcnt lgkmcnt(4)
	v_mfma_f32_16x16x32_bf16 v[12:15], v[56:59], v[134:137], v[12:15]
	ds_write_b128 v153, v[182:185] offset:53248
	global_load_dwordx4 v[174:177], v122, s[98:99] offset:640
	s_waitcnt lgkmcnt(4)
	v_mfma_f32_16x16x32_bf16 v[16:19], v[60:63], v[118:121], v[16:19]
	ds_write_b128 v153, v[186:189] offset:57344
	global_load_dwordx4 v[178:181], v123, s[100:101] offset:640
	v_mfma_f32_16x16x32_bf16 v[20:23], v[60:63], v[126:129], v[20:23]
	ds_write_b128 v153, v[190:193] offset:61440
	global_load_dwordx4 v[182:185], v124, s[100:101] offset:640
	v_mfma_f32_16x16x32_bf16 v[24:27], v[60:63], v[130:133], v[24:27]
	global_load_dwordx4 v[186:189], v150, s[100:101] offset:640
	v_mfma_f32_16x16x32_bf16 v[28:31], v[60:63], v[134:137], v[28:31]
	global_load_dwordx4 v[190:193], v151, s[100:101] offset:640
	s_waitcnt lgkmcnt(0)
	s_barrier
	ds_read_b128 v[32:35], v239 offset:32768
	ds_read_b128 v[40:43], v241 offset:32768
	ds_read_b128 v[44:47], v241 offset:34816
	ds_read_b128 v[48:51], v241 offset:36864
	ds_read_b128 v[52:55], v241 offset:38912
	ds_read_b128 v[36:39], v239 offset:34816
	s_waitcnt lgkmcnt(4)
	v_mfma_f32_16x16x32_bf16 v[0:3], v[32:35], v[40:43], v[0:3]
	ds_read_b128 v[56:59], v240 offset:32768
	s_waitcnt lgkmcnt(4)
	v_mfma_f32_16x16x32_bf16 v[4:7], v[32:35], v[44:47], v[4:7]
	ds_read_b128 v[118:121], v242 offset:32768
	s_waitcnt lgkmcnt(4)
	v_mfma_f32_16x16x32_bf16 v[8:11], v[32:35], v[48:51], v[8:11]
	ds_read_b128 v[126:129], v242 offset:34816
	s_waitcnt lgkmcnt(4)
	v_mfma_f32_16x16x32_bf16 v[12:15], v[32:35], v[52:55], v[12:15]
	ds_read_b128 v[130:133], v242 offset:36864
	s_waitcnt lgkmcnt(4)
	v_mfma_f32_16x16x32_bf16 v[16:19], v[36:39], v[40:43], v[16:19]
	ds_read_b128 v[134:137], v242 offset:38912
	v_mfma_f32_16x16x32_bf16 v[20:23], v[36:39], v[44:47], v[20:23]
	ds_read_b128 v[60:63], v240 offset:34816
	v_mfma_f32_16x16x32_bf16 v[24:27], v[36:39], v[48:51], v[24:27]
	v_mfma_f32_16x16x32_bf16 v[28:31], v[36:39], v[52:55], v[28:31]
	s_waitcnt lgkmcnt(4)
	v_mfma_f32_16x16x32_bf16 v[0:3], v[56:59], v[118:121], v[0:3]
	s_waitcnt vmcnt(6)
	ds_write_b128 v153, v[138:141]
	s_waitcnt lgkmcnt(4)
	v_mfma_f32_16x16x32_bf16 v[4:7], v[56:59], v[126:129], v[4:7]
	ds_write_b128 v153, v[142:145] offset:4096
	s_waitcnt lgkmcnt(4)
	v_mfma_f32_16x16x32_bf16 v[8:11], v[56:59], v[130:133], v[8:11]
	ds_write_b128 v153, v[154:157] offset:16384
	global_load_dwordx4 v[138:141], v116, s[98:99] offset:768
	s_waitcnt lgkmcnt(4)
	v_mfma_f32_16x16x32_bf16 v[12:15], v[56:59], v[134:137], v[12:15]
	ds_write_b128 v153, v[158:161] offset:20480
	global_load_dwordx4 v[142:145], v122, s[98:99] offset:768
	s_waitcnt lgkmcnt(4)
	v_mfma_f32_16x16x32_bf16 v[16:19], v[60:63], v[118:121], v[16:19]
	ds_write_b128 v153, v[162:165] offset:24576
	global_load_dwordx4 v[154:157], v123, s[100:101] offset:768
	v_mfma_f32_16x16x32_bf16 v[20:23], v[60:63], v[126:129], v[20:23]
	ds_write_b128 v153, v[166:169] offset:28672
	global_load_dwordx4 v[158:161], v124, s[100:101] offset:768
	v_mfma_f32_16x16x32_bf16 v[24:27], v[60:63], v[130:133], v[24:27]
	global_load_dwordx4 v[162:165], v150, s[100:101] offset:768
	v_mfma_f32_16x16x32_bf16 v[28:31], v[60:63], v[134:137], v[28:31]
	global_load_dwordx4 v[166:169], v151, s[100:101] offset:768
	s_waitcnt lgkmcnt(0)
	s_barrier
	ds_read_b128 v[32:35], v239
	ds_read_b128 v[40:43], v241
	ds_read_b128 v[44:47], v241 offset:2048
	ds_read_b128 v[48:51], v241 offset:4096
	ds_read_b128 v[52:55], v241 offset:6144
	ds_read_b128 v[36:39], v239 offset:2048
	s_waitcnt lgkmcnt(4)
	v_mfma_f32_16x16x32_bf16 v[0:3], v[32:35], v[40:43], v[0:3]
	ds_read_b128 v[56:59], v240
	s_waitcnt lgkmcnt(4)
	v_mfma_f32_16x16x32_bf16 v[4:7], v[32:35], v[44:47], v[4:7]
	ds_read_b128 v[118:121], v242
	s_waitcnt lgkmcnt(4)
	v_mfma_f32_16x16x32_bf16 v[8:11], v[32:35], v[48:51], v[8:11]
	ds_read_b128 v[126:129], v242 offset:2048
	s_waitcnt lgkmcnt(4)
	v_mfma_f32_16x16x32_bf16 v[12:15], v[32:35], v[52:55], v[12:15]
	ds_read_b128 v[130:133], v242 offset:4096
	s_waitcnt lgkmcnt(4)
	v_mfma_f32_16x16x32_bf16 v[16:19], v[36:39], v[40:43], v[16:19]
	ds_read_b128 v[134:137], v242 offset:6144
	v_mfma_f32_16x16x32_bf16 v[20:23], v[36:39], v[44:47], v[20:23]
	ds_read_b128 v[60:63], v240 offset:2048
	v_mfma_f32_16x16x32_bf16 v[24:27], v[36:39], v[48:51], v[24:27]
	v_mfma_f32_16x16x32_bf16 v[28:31], v[36:39], v[52:55], v[28:31]
	s_waitcnt lgkmcnt(4)
	v_mfma_f32_16x16x32_bf16 v[0:3], v[56:59], v[118:121], v[0:3]
	s_waitcnt vmcnt(6)
	ds_write_b128 v153, v[170:173] offset:32768
	s_waitcnt lgkmcnt(4)
	v_mfma_f32_16x16x32_bf16 v[4:7], v[56:59], v[126:129], v[4:7]
	ds_write_b128 v153, v[174:177] offset:36864
	s_waitcnt lgkmcnt(4)
	v_mfma_f32_16x16x32_bf16 v[8:11], v[56:59], v[130:133], v[8:11]
	ds_write_b128 v153, v[178:181] offset:49152
	global_load_dwordx4 v[170:173], v116, s[98:99] offset:896
	s_waitcnt lgkmcnt(4)
	v_mfma_f32_16x16x32_bf16 v[12:15], v[56:59], v[134:137], v[12:15]
	ds_write_b128 v153, v[182:185] offset:53248
	global_load_dwordx4 v[174:177], v122, s[98:99] offset:896
	s_waitcnt lgkmcnt(4)
	v_mfma_f32_16x16x32_bf16 v[16:19], v[60:63], v[118:121], v[16:19]
	ds_write_b128 v153, v[186:189] offset:57344
	global_load_dwordx4 v[178:181], v123, s[100:101] offset:896
	v_mfma_f32_16x16x32_bf16 v[20:23], v[60:63], v[126:129], v[20:23]
	ds_write_b128 v153, v[190:193] offset:61440
	global_load_dwordx4 v[182:185], v124, s[100:101] offset:896
	v_mfma_f32_16x16x32_bf16 v[24:27], v[60:63], v[130:133], v[24:27]
	global_load_dwordx4 v[186:189], v150, s[100:101] offset:896
	v_mfma_f32_16x16x32_bf16 v[28:31], v[60:63], v[134:137], v[28:31]
	global_load_dwordx4 v[190:193], v151, s[100:101] offset:896
	s_waitcnt lgkmcnt(0)
	s_barrier
	ds_read_b128 v[32:35], v239 offset:32768
	ds_read_b128 v[40:43], v241 offset:32768
	ds_read_b128 v[44:47], v241 offset:34816
	ds_read_b128 v[48:51], v241 offset:36864
	ds_read_b128 v[52:55], v241 offset:38912
	ds_read_b128 v[36:39], v239 offset:34816
	s_waitcnt lgkmcnt(4)
	v_mfma_f32_16x16x32_bf16 v[0:3], v[32:35], v[40:43], v[0:3]
	ds_read_b128 v[56:59], v240 offset:32768
	s_waitcnt lgkmcnt(4)
	v_mfma_f32_16x16x32_bf16 v[4:7], v[32:35], v[44:47], v[4:7]
	ds_read_b128 v[118:121], v242 offset:32768
	s_waitcnt lgkmcnt(4)
	v_mfma_f32_16x16x32_bf16 v[8:11], v[32:35], v[48:51], v[8:11]
	ds_read_b128 v[126:129], v242 offset:34816
	s_waitcnt lgkmcnt(4)
	v_mfma_f32_16x16x32_bf16 v[12:15], v[32:35], v[52:55], v[12:15]
	ds_read_b128 v[130:133], v242 offset:36864
	s_waitcnt lgkmcnt(4)
	v_mfma_f32_16x16x32_bf16 v[16:19], v[36:39], v[40:43], v[16:19]
	ds_read_b128 v[134:137], v242 offset:38912
	v_mfma_f32_16x16x32_bf16 v[20:23], v[36:39], v[44:47], v[20:23]
	ds_read_b128 v[60:63], v240 offset:34816
	v_mfma_f32_16x16x32_bf16 v[24:27], v[36:39], v[48:51], v[24:27]
	v_mfma_f32_16x16x32_bf16 v[28:31], v[36:39], v[52:55], v[28:31]
	s_waitcnt lgkmcnt(4)
	v_mfma_f32_16x16x32_bf16 v[0:3], v[56:59], v[118:121], v[0:3]
	s_waitcnt vmcnt(6)
	ds_write_b128 v153, v[138:141]
	s_waitcnt lgkmcnt(4)
	v_mfma_f32_16x16x32_bf16 v[4:7], v[56:59], v[126:129], v[4:7]
	ds_write_b128 v153, v[142:145] offset:4096
	s_waitcnt lgkmcnt(4)
	v_mfma_f32_16x16x32_bf16 v[8:11], v[56:59], v[130:133], v[8:11]
	ds_write_b128 v153, v[154:157] offset:16384
	s_waitcnt lgkmcnt(4)
	v_mfma_f32_16x16x32_bf16 v[12:15], v[56:59], v[134:137], v[12:15]
	ds_write_b128 v153, v[158:161] offset:20480
	s_waitcnt lgkmcnt(4)
	v_mfma_f32_16x16x32_bf16 v[16:19], v[60:63], v[118:121], v[16:19]
	ds_write_b128 v153, v[162:165] offset:24576
	v_mfma_f32_16x16x32_bf16 v[20:23], v[60:63], v[126:129], v[20:23]
	ds_write_b128 v153, v[166:169] offset:28672
	v_mfma_f32_16x16x32_bf16 v[24:27], v[60:63], v[130:133], v[24:27]
	v_mfma_f32_16x16x32_bf16 v[28:31], v[60:63], v[134:137], v[28:31]
	s_waitcnt lgkmcnt(0)
	s_barrier
	ds_read_b128 v[32:35], v239
	ds_read_b128 v[40:43], v241
	ds_read_b128 v[44:47], v241 offset:2048
	ds_read_b128 v[48:51], v241 offset:4096
	ds_read_b128 v[52:55], v241 offset:6144
	ds_read_b128 v[36:39], v239 offset:2048
	s_waitcnt lgkmcnt(4)
	v_mfma_f32_16x16x32_bf16 v[0:3], v[32:35], v[40:43], v[0:3]
	ds_read_b128 v[56:59], v240
	s_waitcnt lgkmcnt(4)
	v_mfma_f32_16x16x32_bf16 v[4:7], v[32:35], v[44:47], v[4:7]
	ds_read_b128 v[118:121], v242
	s_waitcnt lgkmcnt(4)
	v_mfma_f32_16x16x32_bf16 v[8:11], v[32:35], v[48:51], v[8:11]
	ds_read_b128 v[126:129], v242 offset:2048
	s_waitcnt lgkmcnt(4)
	v_mfma_f32_16x16x32_bf16 v[12:15], v[32:35], v[52:55], v[12:15]
	ds_read_b128 v[130:133], v242 offset:4096
	s_waitcnt lgkmcnt(4)
	v_mfma_f32_16x16x32_bf16 v[16:19], v[36:39], v[40:43], v[16:19]
	ds_read_b128 v[134:137], v242 offset:6144
	v_mfma_f32_16x16x32_bf16 v[20:23], v[36:39], v[44:47], v[20:23]
	ds_read_b128 v[60:63], v240 offset:2048
	v_mfma_f32_16x16x32_bf16 v[24:27], v[36:39], v[48:51], v[24:27]
	v_mfma_f32_16x16x32_bf16 v[28:31], v[36:39], v[52:55], v[28:31]
	s_waitcnt lgkmcnt(4)
	v_mfma_f32_16x16x32_bf16 v[0:3], v[56:59], v[118:121], v[0:3]
	s_waitcnt vmcnt(0)
	ds_write_b128 v153, v[170:173] offset:32768
	s_waitcnt lgkmcnt(4)
	v_mfma_f32_16x16x32_bf16 v[4:7], v[56:59], v[126:129], v[4:7]
	ds_write_b128 v153, v[174:177] offset:36864
	s_waitcnt lgkmcnt(4)
	v_mfma_f32_16x16x32_bf16 v[8:11], v[56:59], v[130:133], v[8:11]
	ds_write_b128 v153, v[178:181] offset:49152
	s_waitcnt lgkmcnt(4)
	v_mfma_f32_16x16x32_bf16 v[12:15], v[56:59], v[134:137], v[12:15]
	ds_write_b128 v153, v[182:185] offset:53248
	s_waitcnt lgkmcnt(4)
	v_mfma_f32_16x16x32_bf16 v[16:19], v[60:63], v[118:121], v[16:19]
	ds_write_b128 v153, v[186:189] offset:57344
	v_mfma_f32_16x16x32_bf16 v[20:23], v[60:63], v[126:129], v[20:23]
	ds_write_b128 v153, v[190:193] offset:61440
	v_mfma_f32_16x16x32_bf16 v[24:27], v[60:63], v[130:133], v[24:27]
	v_mfma_f32_16x16x32_bf16 v[28:31], v[60:63], v[134:137], v[28:31]
	s_waitcnt lgkmcnt(0)
	s_barrier
	ds_read_b128 v[32:35], v239 offset:32768
	ds_read_b128 v[40:43], v241 offset:32768
	ds_read_b128 v[44:47], v241 offset:34816
	ds_read_b128 v[48:51], v241 offset:36864
	ds_read_b128 v[52:55], v241 offset:38912
	ds_read_b128 v[36:39], v239 offset:34816
	s_waitcnt lgkmcnt(4)
	v_mfma_f32_16x16x32_bf16 v[0:3], v[32:35], v[40:43], v[0:3]
	ds_read_b128 v[56:59], v240 offset:32768
	s_waitcnt lgkmcnt(4)
	v_mfma_f32_16x16x32_bf16 v[4:7], v[32:35], v[44:47], v[4:7]
	ds_read_b128 v[118:121], v242 offset:32768
	s_waitcnt lgkmcnt(4)
	v_mfma_f32_16x16x32_bf16 v[8:11], v[32:35], v[48:51], v[8:11]
	ds_read_b128 v[126:129], v242 offset:34816
	s_waitcnt lgkmcnt(4)
	v_mfma_f32_16x16x32_bf16 v[12:15], v[32:35], v[52:55], v[12:15]
	ds_read_b128 v[130:133], v242 offset:36864
	s_waitcnt lgkmcnt(4)
	v_mfma_f32_16x16x32_bf16 v[16:19], v[36:39], v[40:43], v[16:19]
	ds_read_b128 v[134:137], v242 offset:38912
	v_mfma_f32_16x16x32_bf16 v[20:23], v[36:39], v[44:47], v[20:23]
	ds_read_b128 v[60:63], v240 offset:34816
	v_mfma_f32_16x16x32_bf16 v[24:27], v[36:39], v[48:51], v[24:27]
	v_mfma_f32_16x16x32_bf16 v[28:31], v[36:39], v[52:55], v[28:31]
	s_waitcnt lgkmcnt(4)
	v_mfma_f32_16x16x32_bf16 v[0:3], v[56:59], v[118:121], v[0:3]
	s_waitcnt lgkmcnt(3)
	v_mfma_f32_16x16x32_bf16 v[4:7], v[56:59], v[126:129], v[4:7]
	s_waitcnt lgkmcnt(2)
	v_mfma_f32_16x16x32_bf16 v[8:11], v[56:59], v[130:133], v[8:11]
	s_waitcnt lgkmcnt(1)
	v_mfma_f32_16x16x32_bf16 v[12:15], v[56:59], v[134:137], v[12:15]
	s_waitcnt lgkmcnt(0)
	v_mfma_f32_16x16x32_bf16 v[16:19], v[60:63], v[118:121], v[16:19]
	v_mfma_f32_16x16x32_bf16 v[20:23], v[60:63], v[126:129], v[20:23]
	v_mfma_f32_16x16x32_bf16 v[24:27], v[60:63], v[130:133], v[24:27]
	v_mfma_f32_16x16x32_bf16 v[28:31], v[60:63], v[134:137], v[28:31]
	s_waitcnt lgkmcnt(0)
	s_barrier
	s_nop 15
	ds_write_b32 v243, v0
	ds_write_b32 v243, v1 offset:528
	ds_write_b32 v243, v2 offset:1056
	ds_write_b32 v243, v3 offset:1584
	ds_write_b32 v243, v4 offset:64
	ds_write_b32 v243, v5 offset:592
	ds_write_b32 v243, v6 offset:1120
	ds_write_b32 v243, v7 offset:1648
	ds_write_b32 v243, v8 offset:128
	ds_write_b32 v243, v9 offset:656
	ds_write_b32 v243, v10 offset:1184
	ds_write_b32 v243, v11 offset:1712
	ds_write_b32 v243, v12 offset:192
	ds_write_b32 v243, v13 offset:720
	ds_write_b32 v243, v14 offset:1248
	ds_write_b32 v243, v15 offset:1776
	ds_write_b32 v243, v16 offset:8448
	ds_write_b32 v243, v17 offset:8976
	ds_write_b32 v243, v18 offset:9504
	ds_write_b32 v243, v19 offset:10032
	ds_write_b32 v243, v20 offset:8512
	ds_write_b32 v243, v21 offset:9040
	ds_write_b32 v243, v22 offset:9568
	ds_write_b32 v243, v23 offset:10096
	ds_write_b32 v243, v24 offset:8576
	ds_write_b32 v243, v25 offset:9104
	ds_write_b32 v243, v26 offset:9632
	ds_write_b32 v243, v27 offset:10160
	ds_write_b32 v243, v28 offset:8640
	ds_write_b32 v243, v29 offset:9168
	ds_write_b32 v243, v30 offset:9696
	ds_write_b32 v243, v31 offset:10224
	v_readlane_b32 s52, v238, 32
	v_readlane_b32 s53, v238, 33
	v_readlane_b32 s54, v238, 34
	v_readlane_b32 s55, v238, 35
	v_readlane_b32 s56, v238, 36
	v_readlane_b32 s57, v238, 37
	v_readlane_b32 s58, v238, 38
	v_readlane_b32 s59, v238, 39
	v_readlane_b32 s60, v238, 40
	v_readlane_b32 s61, v238, 41
	v_readlane_b32 s62, v238, 42
	v_readlane_b32 s63, v238, 43
	v_readlane_b32 s64, v238, 44
	v_readlane_b32 s65, v238, 45
	v_readlane_b32 s66, v238, 46
	v_readlane_b32 s67, v238, 47
	s_and_b32 s10, s0, 0x7fffffc0
	v_add_lshl_u32 v33, v95, s10, 11
	v_add_lshl_u32 v32, v87, s10, 11
	v_add_lshl_u32 v34, v90, s10, 11
	v_add_lshl_u32 v36, v93, s10, 11
	v_or_b32_e32 v0, s14, v82
	v_lshlrev_b32_e32 v66, 2, v0
	v_lshl_add_u64 v[8:9], s[62:63], 0, v[66:67]
	v_readlane_b32 s52, v236, 32
	v_readlane_b32 s66, v236, 46
	v_readlane_b32 s67, v236, 47
	s_mov_b32 s14, 0
	v_lshl_add_u64 v[10:11], s[66:67], 0, v[66:67]
	v_lshlrev_b32_e32 v66, 1, v0
	v_lshl_add_u64 v[12:13], s[50:51], 0, v[66:67]
	v_mov_b32_e32 v66, v33
	v_readlane_b32 s53, v236, 33
	v_readlane_b32 s54, v236, 34
	v_readlane_b32 s55, v236, 35
	v_readlane_b32 s56, v236, 36
	v_readlane_b32 s57, v236, 37
	v_readlane_b32 s58, v236, 38
	v_readlane_b32 s59, v236, 39
	v_readlane_b32 s60, v236, 40
	v_readlane_b32 s61, v236, 41
	v_readlane_b32 s62, v236, 42
	v_readlane_b32 s63, v236, 43
	v_readlane_b32 s64, v236, 44
	v_readlane_b32 s65, v236, 45
	s_waitcnt lgkmcnt(0)
	s_barrier
